# gdn prep KK^T/QK^T: the four QK^T waves take row blocks in mirrored order so every SIMD carries 5 column-block iterations instead of 2/4/6/8; on top of v47
# speedup vs baseline: 1.0049x; 1.0049x over previous
; #define LAS __attribute__((address_space(3)))
; DI unsigned pk2(float lo, float hi) { f32x2 v = {lo, hi}; bf16x2_t b = __builtin_convertvector(v, bf16x2_t); return __builtin_bit_cast(unsigned, b); }
; DI float lo_bf(unsigned u) { return __uint_as_float(u << 16); }
; DI float hi_bf(unsigned u) { return __uint_as_float(u & 0xffff0000u); }
; DI float siluf_(float x) { return x * __builtin_amdgcn_rcpf(1.f + __expf(-x)); }
; DI void gdn_prep_item(LAS unsigned char* lds, const Ctx& c, int l, int item) {
;     ...
;         unsigned xin[3][11]; f32x2 cwv[3][4];
; #pragma unroll
;         for (int which = 0; which < 3; ++which) {
;             const int cb = which * 512 + h * 128 + 2 * cp;
; #pragma unroll
;             for (int r = 0; r < 11; ++r) { const int sl = n * 64 + 8 * tg - 3 + r; xin[which][r] = sl >= 0 ? *(const unsigned*)(QKV + (size_t)(b * SEQ + sl) * 1536 + cb) : 0u; }
; #pragma unroll
;             for (int j = 0; j < 4; ++j) cwv[which][j] = *(const f32x2*)(c.conv_w + (size_t)l * 4 * 1536 + cb + j * 1536);
;         }
; #pragma unroll
;         for (int which = 0; which < 3; ++which) {
;             float w0[4], w1[4];
; #pragma unroll
;             for (int j = 0; j < 4; ++j) { w0[j] = cwv[which][j].x; w1[j] = cwv[which][j].y; }
;             float x0[11], x1[11];
; #pragma unroll
;             for (int r = 0; r < 11; ++r) { x0[r] = lo_bf(xin[which][r]); x1[r] = hi_bf(xin[which][r]); }
; #pragma unroll
;             for (int t = 0; t < 8; ++t) {
;                 float a0 = 0.f, a1 = 0.f;
; #pragma unroll
;                 for (int j = 0; j < 4; ++j) { a0 += w0[j] * x0[t + j]; a1 += w1[j] * x1[t + j]; }
;                 a0 = siluf_(a0); a1 = siluf_(a1);
;                 const int tl = 8 * tg + t;
;                 if (which < 2) {
;                     const float ss = wave_sum(a0 * a0 + a1 * a1); float rs = __builtin_amdgcn_rsqf(ss + RMS_EPS); if (which == 0) rs *= 0.08838834764831845f;
;                     a0 *= rs; a1 *= rs;
;                     *(LAS unsigned*)(lds + (which == 0 ? GP_QB : GP_KB) + tl * 272 + cp * 4) = pk2(a0, a1);
;                     if (which == 1) { kf[tl * 129 + 2 * cp] = a0; kf[tl * 129 + 2 * cp + 1] = a1; }
;                 } else { vf[tl * 129 + 2 * cp] = a0; vf[tl * 129 + 2 * cp + 1] = a1; }
;             }
.LBB0_278:
	v_lshlrev_b32_e32 v0, 2, v0
	v_lshl_add_u64 v[8:9], s[72:73], 0, v[0:1]
	v_add_co_u32_e32 v4, vcc, 0x1000, v8
	s_waitcnt vmcnt(8)
	v_and_b32_e32 v81, 0xffff0000, v61
	v_addc_co_u32_e32 v5, vcc, 0, v9, vcc
	v_add_co_u32_e32 v6, vcc, 0x3000, v8
	v_lshlrev_b32_e32 v80, 16, v61
	s_nop 0
	v_addc_co_u32_e32 v7, vcc, 0, v9, vcc
	v_add_co_u32_e32 v8, vcc, s63, v8
	v_and_b32_e32 v61, 64, v230
	s_nop 0
	v_addc_co_u32_e32 v9, vcc, 0, v9, vcc
	v_lshlrev_b32_e32 v44, 16, v32
	v_and_b32_e32 v45, 0xffff0000, v32
	v_lshlrev_b32_e32 v40, 16, v33
	v_and_b32_e32 v41, 0xffff0000, v33
	v_lshlrev_b32_e32 v32, 16, v62
	v_and_b32_e32 v33, 0xffff0000, v62
	v_add_u32_e32 v61, 64, v61
	v_xor_b32_e32 v62, 1, v230
	v_cmp_lt_i32_e32 vcc, v62, v61
	v_lshlrev_b32_e32 v48, 16, v31
	v_and_b32_e32 v49, 0xffff0000, v31
	v_cndmask_b32_e32 v62, v230, v62, vcc
	v_lshlrev_b32_e32 v66, 2, v62
	v_xor_b32_e32 v62, 2, v230
	v_cmp_lt_i32_e32 vcc, v62, v61
	s_waitcnt vmcnt(7)
	v_pk_fma_f32 v[80:81], v[18:19], v[80:81], 0 op_sel_hi:[1,1,0]
	v_lshlrev_b32_e32 v46, 16, v30
	v_cndmask_b32_e32 v62, v230, v62, vcc
	v_lshlrev_b32_e32 v65, 2, v62
	v_xor_b32_e32 v62, 4, v230
	v_cmp_lt_i32_e32 vcc, v62, v61
	v_and_b32_e32 v47, 0xffff0000, v30
	v_lshlrev_b32_e32 v42, 16, v34
	v_cndmask_b32_e32 v62, v230, v62, vcc
	v_lshlrev_b32_e32 v64, 2, v62
	v_xor_b32_e32 v62, 8, v230
	v_cmp_lt_i32_e32 vcc, v62, v61
	v_and_b32_e32 v43, 0xffff0000, v34
	v_lshlrev_b32_e32 v38, 16, v36
	v_cndmask_b32_e32 v62, v230, v62, vcc
	v_and_b32_e32 v39, 0xffff0000, v36
	v_lshlrev_b32_e32 v30, 16, v35
	v_and_b32_e32 v31, 0xffff0000, v35
	v_lshlrev_b32_e32 v34, 16, v37
	v_and_b32_e32 v35, 0xffff0000, v37
	v_lshlrev_b32_e32 v36, 16, v63
	v_and_b32_e32 v37, 0xffff0000, v63
	v_lshlrev_b32_e32 v63, 2, v62
	v_xor_b32_e32 v62, 16, v230
	s_waitcnt vmcnt(6)
	v_pk_fma_f32 v[80:81], v[20:21], v[48:49], v[80:81]
	v_cmp_lt_i32_e32 vcc, v62, v61
	v_xor_b32_e32 v79, 32, v230
	s_waitcnt vmcnt(5)
	v_pk_fma_f32 v[80:81], v[22:23], v[46:47], v[80:81]
	v_cndmask_b32_e32 v62, v230, v62, vcc
	v_cmp_lt_i32_e32 vcc, v79, v61
	s_waitcnt vmcnt(4)
	v_pk_fma_f32 v[80:81], v[24:25], v[44:45], v[80:81]
	v_lshlrev_b32_e32 v62, 2, v62
	v_cndmask_b32_e32 v61, v230, v79, vcc
	v_mul_f32_e32 v79, 0xbfb8aa3b, v81
	v_exp_f32_e32 v79, v79
	v_lshlrev_b32_e32 v61, 2, v61
	s_lshr_b32 s4, s33, 2
	s_and_b32 s4, s4, 0x7f
	v_add_f32_e32 v79, 1.0, v79
	v_rcp_f32_e32 v83, v79
	v_mul_f32_e32 v79, 0xbfb8aa3b, v80
	v_exp_f32_e32 v79, v79
	global_load_dwordx2 v[2:3], v0, s[72:73]
	v_pk_fma_f32 v[48:49], v[18:19], v[48:49], 0 op_sel_hi:[1,1,0]
	global_load_dwordx2 v[4:5], v[4:5], off offset:2048
	v_add_f32_e32 v79, 1.0, v79
	v_rcp_f32_e32 v82, v79
	global_load_dwordx2 v[6:7], v[6:7], off
	s_lshl_b32 s10, s4, 13
	global_load_dwordx2 v[8:9], v[8:9], off offset:2048
	v_pk_mul_f32 v[80:81], v[80:81], v[82:83]
	v_lshlrev_b32_e32 v0, 2, v27
	v_pk_mul_f32 v[82:83], v[80:81], v[80:81]
	v_add_u32_e32 v28, 0, v0
	v_add_f32_e32 v79, v83, v82
	s_nop 1
	v_mov_b32_dpp v82, v79 quad_perm:[1,0,3,2] row_mask:0xf bank_mask:0xf
	v_readlane_b32 s4, v254, 4
	v_pk_fma_f32 v[48:49], v[20:21], v[46:47], v[48:49]
	v_add_u32_e32 v67, v28, v0
	v_lshl_add_u32 v0, v27, 3, s4
	s_waitcnt lgkmcnt(0)
	v_add_f32_e32 v79, v79, v82
	s_nop 1
	v_mov_b32_dpp v82, v79 quad_perm:[2,3,0,1] row_mask:0xf bank_mask:0xf
	s_mul_i32 s4, s83, 0x880
	v_pk_fma_f32 v[48:49], v[22:23], v[44:45], v[48:49]
	v_pk_fma_f32 v[46:47], v[18:19], v[46:47], 0 op_sel_hi:[1,1,0]
	v_pk_fma_f32 v[48:49], v[24:25], v[42:43], v[48:49]
	s_waitcnt lgkmcnt(0)
	v_add_f32_e32 v79, v79, v82
	s_nop 1
	v_mov_b32_dpp v82, v79 row_half_mirror row_mask:0xf bank_mask:0xf
	v_pk_fma_f32 v[46:47], v[20:21], v[44:45], v[46:47]
	v_pk_fma_f32 v[44:45], v[18:19], v[44:45], 0 op_sel_hi:[1,1,0]
	v_pk_fma_f32 v[46:47], v[22:23], v[42:43], v[46:47]
	v_pk_fma_f32 v[44:45], v[20:21], v[42:43], v[44:45]
	s_waitcnt lgkmcnt(0)
	v_add_f32_e32 v79, v79, v82
	s_nop 1
	v_mov_b32_dpp v82, v79 row_mirror row_mask:0xf bank_mask:0xf
	v_pk_fma_f32 v[46:47], v[24:25], v[40:41], v[46:47]
	v_pk_fma_f32 v[44:45], v[22:23], v[40:41], v[44:45]
	v_pk_fma_f32 v[42:43], v[18:19], v[42:43], 0 op_sel_hi:[1,1,0]
	v_pk_fma_f32 v[44:45], v[24:25], v[38:39], v[44:45]
	s_waitcnt lgkmcnt(0)
	v_add_f32_e32 v79, v79, v82
	v_mov_b32_e32 v82, v79
	v_mov_b32_e32 v89, v79
	s_nop 1
	v_permlane16_swap_b32_e32 v82, v89
	s_nop 1
	v_mov_b32_dpp v82, v89 quad_perm:[0,1,2,3] row_mask:0x5 bank_mask:0xf
	v_pk_fma_f32 v[42:43], v[20:21], v[40:41], v[42:43]
	v_pk_fma_f32 v[40:41], v[18:19], v[40:41], 0 op_sel_hi:[1,1,0]
	v_pk_fma_f32 v[42:43], v[22:23], v[38:39], v[42:43]
	v_pk_fma_f32 v[40:41], v[20:21], v[38:39], v[40:41]
	s_waitcnt lgkmcnt(0)
	v_add_f32_e32 v79, v79, v82
	v_mov_b32_e32 v82, v79
	v_mov_b32_e32 v89, v79
	s_nop 1
	v_permlane32_swap_b32_e32 v82, v89
	s_nop 1
	v_mov_b32_dpp v82, v89 quad_perm:[0,1,2,3] row_mask:0x3 bank_mask:0xf
	v_pk_fma_f32 v[42:43], v[24:25], v[30:31], v[42:43]
	v_pk_fma_f32 v[40:41], v[22:23], v[30:31], v[40:41]
	v_pk_fma_f32 v[38:39], v[18:19], v[38:39], 0 op_sel_hi:[1,1,0]
	v_pk_fma_f32 v[40:41], v[24:25], v[32:33], v[40:41]
	s_waitcnt lgkmcnt(0)
; #define LAS __attribute__((address_space(3)))
; DI unsigned pk2(float lo, float hi) { f32x2 v = {lo, hi}; bf16x2_t b = __builtin_convertvector(v, bf16x2_t); return __builtin_bit_cast(unsigned, b); }
; DI float lo_bf(unsigned u) { return __uint_as_float(u << 16); }
; DI float hi_bf(unsigned u) { return __uint_as_float(u & 0xffff0000u); }
; DI float siluf_(float x) { return x * __builtin_amdgcn_rcpf(1.f + __expf(-x)); }
; DI void gdn_prep_item(LAS unsigned char* lds, const Ctx& c, int l, int item) {
;     ...
; #pragma unroll
;         for (int which = 0; which < 3; ++which) {
;             float w0[4], w1[4];
; #pragma unroll
;             for (int j = 0; j < 4; ++j) { w0[j] = cwv[which][j].x; w1[j] = cwv[which][j].y; }
;             float x0[11], x1[11];
; #pragma unroll
;             for (int r = 0; r < 11; ++r) { x0[r] = lo_bf(xin[which][r]); x1[r] = hi_bf(xin[which][r]); }
; #pragma unroll
;             for (int t = 0; t < 8; ++t) {
;                 float a0 = 0.f, a1 = 0.f;
; #pragma unroll
;                 for (int j = 0; j < 4; ++j) { a0 += w0[j] * x0[t + j]; a1 += w1[j] * x1[t + j]; }
;                 a0 = siluf_(a0); a1 = siluf_(a1);
;                 const int tl = 8 * tg + t;
;                 if (which < 2) {
;                     const float ss = wave_sum(a0 * a0 + a1 * a1); float rs = __builtin_amdgcn_rsqf(ss + RMS_EPS); if (which == 0) rs *= 0.08838834764831845f;
;                     a0 *= rs; a1 *= rs;
;                     *(LAS unsigned*)(lds + (which == 0 ? GP_QB : GP_KB) + tl * 272 + cp * 4) = pk2(a0, a1);
;                     if (which == 1) { kf[tl * 129 + 2 * cp] = a0; kf[tl * 129 + 2 * cp + 1] = a1; }
;                 } else { vf[tl * 129 + 2 * cp] = a0; vf[tl * 129 + 2 * cp + 1] = a1; }
;             }
;     ...
;         const int mat = wave >> 2, rb = wave & 3, m16 = lane & 15, g4 = lane >> 4;
;         const LAS unsigned char* Ab = lds + (mat == 0 ? GP_KB : GP_QB) + (16 * rb + m16) * 272 + g4 * 16;
	v_add_f32_e32 v79, v79, v82
	v_add_f32_e32 v79, 0x358637bd, v79
	v_rsq_f32_e32 v79, v79
	v_pk_fma_f32 v[38:39], v[20:21], v[30:31], v[38:39]
	v_pk_fma_f32 v[18:19], v[18:19], v[30:31], 0 op_sel_hi:[1,1,0]
	v_pk_fma_f32 v[38:39], v[22:23], v[32:33], v[38:39]
	v_mul_f32_e32 v82, 0x3db504f3, v79
	v_pk_mul_f32 v[80:81], v[80:81], v[82:83] op_sel_hi:[1,0]
	v_add_u32_e32 v79, s4, v28
	v_cvt_pk_bf16_f32 v80, v80, v81
	ds_write_b32 v79, v80
	v_mul_f32_e32 v80, 0xbfb8aa3b, v49
	v_exp_f32_e32 v80, v80
	s_or_b32 s4, s86, 1
	s_mul_i32 s5, s4, 0x110
	v_pk_fma_f32 v[38:39], v[24:25], v[34:35], v[38:39]
	v_add_f32_e32 v80, 1.0, v80
	v_rcp_f32_e32 v81, v80
	v_mul_f32_e32 v80, 0xbfb8aa3b, v48
	v_exp_f32_e32 v80, v80
	v_pk_fma_f32 v[18:19], v[20:21], v[32:33], v[18:19]
	s_mulk_i32 s83, 0x1020
	v_pk_fma_f32 v[18:19], v[22:23], v[34:35], v[18:19]
	v_add_f32_e32 v80, 1.0, v80
	v_rcp_f32_e32 v80, v80
	v_pk_fma_f32 v[18:19], v[24:25], v[36:37], v[18:19]
	v_lshlrev_b32_e32 v36, 16, v72
	v_and_b32_e32 v37, 0xffff0000, v72
	v_pk_mul_f32 v[48:49], v[48:49], v[80:81]
	v_mul_f32_e32 v20, 0xbfb8aa3b, v19
	v_pk_mul_f32 v[80:81], v[48:49], v[48:49]
	v_exp_f32_e32 v20, v20
	v_add_f32_e32 v80, v81, v80
	s_nop 1
	v_mov_b32_dpp v81, v80 quad_perm:[1,0,3,2] row_mask:0xf bank_mask:0xf
	v_lshlrev_b32_e32 v34, 16, v71
	v_add_f32_e32 v20, 1.0, v20
	v_rcp_f32_e32 v21, v20
	v_mul_f32_e32 v20, 0xbfb8aa3b, v18
	s_waitcnt lgkmcnt(0)
	v_add_f32_e32 v80, v80, v81
	s_nop 1
	v_mov_b32_dpp v81, v80 quad_perm:[2,3,0,1] row_mask:0xf bank_mask:0xf
	v_exp_f32_e32 v20, v20
	v_and_b32_e32 v35, 0xffff0000, v71
	s_mulk_i32 s4, 0x204
	v_lshlrev_b32_e32 v32, 16, v74
	s_waitcnt lgkmcnt(0)
	v_add_f32_e32 v80, v80, v81
	s_nop 1
	v_mov_b32_dpp v81, v80 row_half_mirror row_mask:0xf bank_mask:0xf
	v_add_f32_e32 v20, 1.0, v20
	v_rcp_f32_e32 v20, v20
	v_and_b32_e32 v33, 0xffff0000, v74
	v_lshlrev_b32_e32 v30, 16, v73
	s_waitcnt lgkmcnt(0)
	v_add_f32_e32 v80, v80, v81
	s_nop 1
	v_mov_b32_dpp v81, v80 row_mirror row_mask:0xf bank_mask:0xf
	v_pk_mul_f32 v[18:19], v[18:19], v[20:21]
	v_and_b32_e32 v31, 0xffff0000, v73
	v_pk_mul_f32 v[20:21], v[18:19], v[18:19]
	s_add_i32 s6, s4, 0x408
	s_waitcnt lgkmcnt(0)
	v_add_f32_e32 v80, v80, v81
	v_mov_b32_e32 v81, v80
	v_mov_b32_e32 v89, v80
	s_nop 1
	v_permlane16_swap_b32_e32 v81, v89
	s_nop 1
	v_mov_b32_dpp v81, v89 quad_perm:[0,1,2,3] row_mask:0x5 bank_mask:0xf
	v_add_f32_e32 v20, v21, v20
	s_nop 1
	v_mov_b32_dpp v21, v20 quad_perm:[1,0,3,2] row_mask:0xf bank_mask:0xf
	s_add_i32 s7, s4, 0x60c
	s_add_i32 s9, s4, 0x810
	s_waitcnt lgkmcnt(0)
	v_add_f32_e32 v80, v80, v81
	v_mov_b32_e32 v81, v80
	v_mov_b32_e32 v89, v80
	s_nop 1
	v_permlane32_swap_b32_e32 v81, v89
	s_nop 1
	v_mov_b32_dpp v81, v89 quad_perm:[0,1,2,3] row_mask:0x3 bank_mask:0xf
	s_waitcnt lgkmcnt(0)
	v_add_f32_e32 v20, v20, v21
	s_nop 1
	v_mov_b32_dpp v21, v20 quad_perm:[2,3,0,1] row_mask:0xf bank_mask:0xf
	v_lshlrev_b32_e32 v22, 16, v78
	v_and_b32_e32 v23, 0xffff0000, v78
	s_waitcnt lgkmcnt(0)
	v_add_f32_e32 v80, v80, v81
	v_add_f32_e32 v80, 0x358637bd, v80
	v_rsq_f32_e32 v80, v80
	s_waitcnt lgkmcnt(0)
	v_add_f32_e32 v20, v20, v21
	s_nop 1
	v_mov_b32_dpp v21, v20 row_half_mirror row_mask:0xf bank_mask:0xf
	v_lshlrev_b32_e32 v24, 16, v77
	v_mul_f32_e32 v80, 0x3db504f3, v80
	v_pk_mul_f32 v[48:49], v[48:49], v[80:81] op_sel_hi:[1,0]
	v_mul_f32_e32 v80, 0xbfb8aa3b, v47
	v_exp_f32_e32 v80, v80
	v_cvt_pk_bf16_f32 v49, v48, v49
	v_add_u32_e32 v48, s5, v28
	s_waitcnt lgkmcnt(0)
	v_add_f32_e32 v20, v20, v21
	v_add_f32_e32 v80, 1.0, v80
	v_rcp_f32_e32 v81, v80
	v_mul_f32_e32 v80, 0xbfb8aa3b, v46
	v_exp_f32_e32 v80, v80
	s_nop 1
	v_mov_b32_dpp v21, v20 row_mirror row_mask:0xf bank_mask:0xf
	s_add_i32 s5, s4, 0x204
	v_and_b32_e32 v25, 0xffff0000, v77
	v_add_f32_e32 v80, 1.0, v80
	v_rcp_f32_e32 v80, v80
	s_waitcnt lgkmcnt(0)
	v_add_f32_e32 v20, v20, v21
	v_mov_b32_e32 v21, v20
	v_mov_b32_e32 v89, v20
	s_nop 1
	v_permlane16_swap_b32_e32 v21, v89
	s_nop 1
	v_mov_b32_dpp v21, v89 quad_perm:[0,1,2,3] row_mask:0x5 bank_mask:0xf
	s_add_i32 s11, s4, 0xa14
	v_pk_mul_f32 v[46:47], v[46:47], v[80:81]
	s_add_i32 s14, s4, 0xc18
	v_pk_mul_f32 v[80:81], v[46:47], v[46:47]
	s_waitcnt lgkmcnt(0)
	v_add_f32_e32 v20, v20, v21
	v_add_f32_e32 v80, v81, v80
	s_nop 1
	v_mov_b32_dpp v81, v80 quad_perm:[1,0,3,2] row_mask:0xf bank_mask:0xf
	v_mov_b32_e32 v21, v20
	v_mov_b32_e32 v89, v20
	s_nop 1
	v_permlane32_swap_b32_e32 v21, v89
	s_nop 1
	v_mov_b32_dpp v21, v89 quad_perm:[0,1,2,3] row_mask:0x3 bank_mask:0xf
	s_and_b32 s8, s2, 3
	s_lshl_b32 s24, s84, 2
	s_bfe_u32 s43, s82, 0x20006
	s_cmp_lt_u32 s82, 0x100
	s_cbranch_scc1 .Lrb_keep
	s_sub_u32 s43, 3, s43
; #define LAS __attribute__((address_space(3)))
; DI unsigned pk2(float lo, float hi) { f32x2 v = {lo, hi}; bf16x2_t b = __builtin_convertvector(v, bf16x2_t); return __builtin_bit_cast(unsigned, b); }
; DI float lo_bf(unsigned u) { return __uint_as_float(u << 16); }
; DI float hi_bf(unsigned u) { return __uint_as_float(u & 0xffff0000u); }
; DI float siluf_(float x) { return x * __builtin_amdgcn_rcpf(1.f + __expf(-x)); }
; DI void gdn_prep_item(LAS unsigned char* lds, const Ctx& c, int l, int item) {
;     ...
; #pragma unroll
;         for (int which = 0; which < 3; ++which) {
;             float w0[4], w1[4];
; #pragma unroll
;             for (int j = 0; j < 4; ++j) { w0[j] = cwv[which][j].x; w1[j] = cwv[which][j].y; }
;             float x0[11], x1[11];
; #pragma unroll
;             for (int r = 0; r < 11; ++r) { x0[r] = lo_bf(xin[which][r]); x1[r] = hi_bf(xin[which][r]); }
; #pragma unroll
;             for (int t = 0; t < 8; ++t) {
;                 float a0 = 0.f, a1 = 0.f;
; #pragma unroll
;                 for (int j = 0; j < 4; ++j) { a0 += w0[j] * x0[t + j]; a1 += w1[j] * x1[t + j]; }
;                 a0 = siluf_(a0); a1 = siluf_(a1);
;                 const int tl = 8 * tg + t;
;                 if (which < 2) {
;                     const float ss = wave_sum(a0 * a0 + a1 * a1); float rs = __builtin_amdgcn_rsqf(ss + RMS_EPS); if (which == 0) rs *= 0.08838834764831845f;
;                     a0 *= rs; a1 *= rs;
;                     *(LAS unsigned*)(lds + (which == 0 ? GP_QB : GP_KB) + tl * 272 + cp * 4) = pk2(a0, a1);
;                     if (which == 1) { kf[tl * 129 + 2 * cp] = a0; kf[tl * 129 + 2 * cp + 1] = a1; }
;                 } else { vf[tl * 129 + 2 * cp] = a0; vf[tl * 129 + 2 * cp + 1] = a1; }
;             }
.Lrb_keep:
	s_waitcnt lgkmcnt(0)
	v_add_f32_e32 v80, v80, v81
	s_nop 1
	v_mov_b32_dpp v81, v80 quad_perm:[2,3,0,1] row_mask:0xf bank_mask:0xf
	s_waitcnt lgkmcnt(0)
	v_add_f32_e32 v20, v20, v21
	v_add_f32_e32 v20, 0x358637bd, v20
	v_rsq_f32_e32 v20, v20
	s_cmpk_gt_u32 s82, 0xff
	s_waitcnt lgkmcnt(0)
	v_add_f32_e32 v80, v80, v81
	s_nop 1
	v_mov_b32_dpp v81, v80 row_half_mirror row_mask:0xf bank_mask:0xf
	v_mul_f32_e32 v20, 0x3db504f3, v20
	v_pk_mul_f32 v[18:19], v[18:19], v[20:21] op_sel_hi:[1,0]
	v_lshlrev_b32_e32 v20, 16, v75
	v_cvt_pk_bf16_f32 v18, v18, v19
	s_waitcnt lgkmcnt(0)
	v_add_f32_e32 v80, v80, v81
	s_nop 1
	v_mov_b32_dpp v81, v80 row_mirror row_mask:0xf bank_mask:0xf
	v_and_b32_e32 v19, 0xffff0000, v76
	v_and_b32_e32 v21, 0xffff0000, v75
	s_waitcnt lgkmcnt(0)
	v_add_f32_e32 v80, v80, v81
	v_mov_b32_e32 v81, v80
	v_mov_b32_e32 v89, v80
	s_nop 1
	v_permlane16_swap_b32_e32 v81, v89
	s_nop 1
	v_mov_b32_dpp v81, v89 quad_perm:[0,1,2,3] row_mask:0x5 bank_mask:0xf
	s_waitcnt lgkmcnt(0)
	v_add_f32_e32 v80, v80, v81
	v_mov_b32_e32 v81, v80
	v_mov_b32_e32 v89, v80
	s_nop 1
	v_permlane32_swap_b32_e32 v81, v89
	s_nop 1
	v_mov_b32_dpp v81, v89 quad_perm:[0,1,2,3] row_mask:0x3 bank_mask:0xf
	s_waitcnt lgkmcnt(0)
	v_add_f32_e32 v80, v80, v81
	v_add_f32_e32 v80, 0x358637bd, v80
	v_rsq_f32_e32 v80, v80
	s_nop 0
	v_mul_f32_e32 v80, 0x3db504f3, v80
	v_pk_mul_f32 v[46:47], v[46:47], v[80:81] op_sel_hi:[1,0]
	s_nop 0
	v_cvt_pk_bf16_f32 v46, v46, v47
	ds_write2_b32 v48, v49, v46 offset1:68
	v_mul_f32_e32 v46, 0xbfb8aa3b, v45
	v_exp_f32_e32 v46, v46
	s_nop 0
	v_add_f32_e32 v46, 1.0, v46
	v_rcp_f32_e32 v47, v46
	v_mul_f32_e32 v46, 0xbfb8aa3b, v44
	v_exp_f32_e32 v46, v46
	s_nop 0
	v_add_f32_e32 v46, 1.0, v46
	v_rcp_f32_e32 v46, v46
	s_nop 0
	v_pk_mul_f32 v[44:45], v[44:45], v[46:47]
	s_nop 0
	v_pk_mul_f32 v[46:47], v[44:45], v[44:45]
	s_nop 0
	v_add_f32_e32 v46, v47, v46
	s_nop 1
	v_mov_b32_dpp v47, v46 quad_perm:[1,0,3,2] row_mask:0xf bank_mask:0xf
	s_waitcnt lgkmcnt(0)
	v_add_f32_e32 v46, v46, v47
	s_nop 1
	v_mov_b32_dpp v47, v46 quad_perm:[2,3,0,1] row_mask:0xf bank_mask:0xf
	s_waitcnt lgkmcnt(0)
	v_add_f32_e32 v46, v46, v47
	s_nop 1
	v_mov_b32_dpp v47, v46 row_half_mirror row_mask:0xf bank_mask:0xf
	s_waitcnt lgkmcnt(0)
	v_add_f32_e32 v46, v46, v47
	s_nop 1
	v_mov_b32_dpp v47, v46 row_mirror row_mask:0xf bank_mask:0xf
	s_waitcnt lgkmcnt(0)
	v_add_f32_e32 v46, v46, v47
	v_mov_b32_e32 v47, v46
	v_mov_b32_e32 v89, v46
	s_nop 1
	v_permlane16_swap_b32_e32 v47, v89
	s_nop 1
	v_mov_b32_dpp v47, v89 quad_perm:[0,1,2,3] row_mask:0x5 bank_mask:0xf
	s_waitcnt lgkmcnt(0)
	v_add_f32_e32 v46, v46, v47
	v_mov_b32_e32 v47, v46
	v_mov_b32_e32 v89, v46
	s_nop 1
	v_permlane32_swap_b32_e32 v47, v89
	s_nop 1
	v_mov_b32_dpp v47, v89 quad_perm:[0,1,2,3] row_mask:0x3 bank_mask:0xf
	s_waitcnt lgkmcnt(0)
	v_add_f32_e32 v46, v46, v47
	v_add_f32_e32 v46, 0x358637bd, v46
	v_rsq_f32_e32 v46, v46
	s_nop 0
	v_mul_f32_e32 v46, 0x3db504f3, v46
	v_pk_mul_f32 v[44:45], v[44:45], v[46:47] op_sel_hi:[1,0]
	s_nop 0
	v_cvt_pk_bf16_f32 v46, v44, v45
	v_mul_f32_e32 v44, 0xbfb8aa3b, v43
	v_exp_f32_e32 v44, v44
	s_nop 0
	v_add_f32_e32 v44, 1.0, v44
	v_rcp_f32_e32 v45, v44
	v_mul_f32_e32 v44, 0xbfb8aa3b, v42
	v_exp_f32_e32 v44, v44
	s_nop 0
	v_add_f32_e32 v44, 1.0, v44
	v_rcp_f32_e32 v44, v44
	s_nop 0
	v_pk_mul_f32 v[42:43], v[42:43], v[44:45]
	s_nop 0
	v_pk_mul_f32 v[44:45], v[42:43], v[42:43]
	s_nop 0
	v_add_f32_e32 v44, v45, v44
	s_nop 1
	v_mov_b32_dpp v45, v44 quad_perm:[1,0,3,2] row_mask:0xf bank_mask:0xf
	s_waitcnt lgkmcnt(0)
	v_add_f32_e32 v44, v44, v45
	s_nop 1
	v_mov_b32_dpp v45, v44 quad_perm:[2,3,0,1] row_mask:0xf bank_mask:0xf
	s_waitcnt lgkmcnt(0)
	v_add_f32_e32 v44, v44, v45
	s_nop 1
	v_mov_b32_dpp v45, v44 row_half_mirror row_mask:0xf bank_mask:0xf
	s_waitcnt lgkmcnt(0)
	v_add_f32_e32 v44, v44, v45
	s_nop 1
	v_mov_b32_dpp v45, v44 row_mirror row_mask:0xf bank_mask:0xf
	s_waitcnt lgkmcnt(0)
	v_add_f32_e32 v44, v44, v45
	v_mov_b32_e32 v45, v44
	v_mov_b32_e32 v89, v44
	s_nop 1
	v_permlane16_swap_b32_e32 v45, v89
	s_nop 1
	v_mov_b32_dpp v45, v89 quad_perm:[0,1,2,3] row_mask:0x5 bank_mask:0xf
	s_waitcnt lgkmcnt(0)
	v_add_f32_e32 v44, v44, v45
	v_mov_b32_e32 v45, v44
	v_mov_b32_e32 v89, v44
	s_nop 1
	v_permlane32_swap_b32_e32 v45, v89
	s_nop 1
	v_mov_b32_dpp v45, v89 quad_perm:[0,1,2,3] row_mask:0x3 bank_mask:0xf
	s_waitcnt lgkmcnt(0)
	v_add_f32_e32 v44, v44, v45
	v_add_f32_e32 v44, 0x358637bd, v44
	v_rsq_f32_e32 v44, v44
	s_nop 0
	v_mul_f32_e32 v44, 0x3db504f3, v44
	v_pk_mul_f32 v[42:43], v[42:43], v[44:45] op_sel_hi:[1,0]
	s_nop 0
	v_cvt_pk_bf16_f32 v42, v42, v43
	ds_write2_b32 v48, v46, v42 offset0:136 offset1:204
	v_mul_f32_e32 v42, 0xbfb8aa3b, v41
	v_exp_f32_e32 v42, v42
	v_add_u32_e32 v46, s83, v67
	v_add_f32_e32 v42, 1.0, v42
	v_rcp_f32_e32 v43, v42
	v_mul_f32_e32 v42, 0xbfb8aa3b, v40
	v_exp_f32_e32 v42, v42
	s_nop 0
	v_add_f32_e32 v42, 1.0, v42
	v_rcp_f32_e32 v42, v42
	s_nop 0
	v_pk_mul_f32 v[40:41], v[40:41], v[42:43]
	s_nop 0
	v_pk_mul_f32 v[42:43], v[40:41], v[40:41]
	s_nop 0
	v_add_f32_e32 v42, v43, v42
	s_nop 1
	v_mov_b32_dpp v43, v42 quad_perm:[1,0,3,2] row_mask:0xf bank_mask:0xf
	s_waitcnt lgkmcnt(0)
	v_add_f32_e32 v42, v42, v43
	s_nop 1
	v_mov_b32_dpp v43, v42 quad_perm:[2,3,0,1] row_mask:0xf bank_mask:0xf
	s_waitcnt lgkmcnt(0)
	v_add_f32_e32 v42, v42, v43
	s_nop 1
	v_mov_b32_dpp v43, v42 row_half_mirror row_mask:0xf bank_mask:0xf
	s_waitcnt lgkmcnt(0)
	v_add_f32_e32 v42, v42, v43
	s_nop 1
	v_mov_b32_dpp v43, v42 row_mirror row_mask:0xf bank_mask:0xf
	s_waitcnt lgkmcnt(0)
; #define LAS __attribute__((address_space(3)))
; DI unsigned pk2(float lo, float hi) { f32x2 v = {lo, hi}; bf16x2_t b = __builtin_convertvector(v, bf16x2_t); return __builtin_bit_cast(unsigned, b); }
; DI float lo_bf(unsigned u) { return __uint_as_float(u << 16); }
; DI float hi_bf(unsigned u) { return __uint_as_float(u & 0xffff0000u); }
; DI float siluf_(float x) { return x * __builtin_amdgcn_rcpf(1.f + __expf(-x)); }
; DI void gdn_prep_item(LAS unsigned char* lds, const Ctx& c, int l, int item) {
;     ...
; #pragma unroll
;         for (int which = 0; which < 3; ++which) {
;             float w0[4], w1[4];
; #pragma unroll
;             for (int j = 0; j < 4; ++j) { w0[j] = cwv[which][j].x; w1[j] = cwv[which][j].y; }
;             float x0[11], x1[11];
; #pragma unroll
;             for (int r = 0; r < 11; ++r) { x0[r] = lo_bf(xin[which][r]); x1[r] = hi_bf(xin[which][r]); }
; #pragma unroll
;             for (int t = 0; t < 8; ++t) {
;                 float a0 = 0.f, a1 = 0.f;
; #pragma unroll
;                 for (int j = 0; j < 4; ++j) { a0 += w0[j] * x0[t + j]; a1 += w1[j] * x1[t + j]; }
;                 a0 = siluf_(a0); a1 = siluf_(a1);
;                 const int tl = 8 * tg + t;
;                 if (which < 2) {
;                     const float ss = wave_sum(a0 * a0 + a1 * a1); float rs = __builtin_amdgcn_rsqf(ss + RMS_EPS); if (which == 0) rs *= 0.08838834764831845f;
;                     a0 *= rs; a1 *= rs;
;                     *(LAS unsigned*)(lds + (which == 0 ? GP_QB : GP_KB) + tl * 272 + cp * 4) = pk2(a0, a1);
;                     if (which == 1) { kf[tl * 129 + 2 * cp] = a0; kf[tl * 129 + 2 * cp + 1] = a1; }
;                 } else { vf[tl * 129 + 2 * cp] = a0; vf[tl * 129 + 2 * cp + 1] = a1; }
;             }
	v_add_f32_e32 v42, v42, v43
	v_mov_b32_e32 v43, v42
	v_mov_b32_e32 v89, v42
	s_nop 1
	v_permlane16_swap_b32_e32 v43, v89
	s_nop 1
	v_mov_b32_dpp v43, v89 quad_perm:[0,1,2,3] row_mask:0x5 bank_mask:0xf
	s_waitcnt lgkmcnt(0)
	v_add_f32_e32 v42, v42, v43
	v_mov_b32_e32 v43, v42
	v_mov_b32_e32 v89, v42
	s_nop 1
	v_permlane32_swap_b32_e32 v43, v89
	s_nop 1
	v_mov_b32_dpp v43, v89 quad_perm:[0,1,2,3] row_mask:0x3 bank_mask:0xf
	s_waitcnt lgkmcnt(0)
	v_add_f32_e32 v42, v42, v43
	v_add_f32_e32 v42, 0x358637bd, v42
	v_rsq_f32_e32 v42, v42
	s_nop 0
	v_mul_f32_e32 v42, 0x3db504f3, v42
	v_pk_mul_f32 v[40:41], v[40:41], v[42:43] op_sel_hi:[1,0]
	v_and_b32_e32 v43, 0xffff0000, v68
	v_cvt_pk_bf16_f32 v42, v40, v41
	v_mul_f32_e32 v40, 0xbfb8aa3b, v39
	v_exp_f32_e32 v40, v40
	s_nop 0
	v_add_f32_e32 v40, 1.0, v40
	v_rcp_f32_e32 v41, v40
	v_mul_f32_e32 v40, 0xbfb8aa3b, v38
	v_exp_f32_e32 v40, v40
	s_nop 0
	v_add_f32_e32 v40, 1.0, v40
	v_rcp_f32_e32 v40, v40
	s_nop 0
	v_pk_mul_f32 v[38:39], v[38:39], v[40:41]
	s_nop 0
	v_pk_mul_f32 v[40:41], v[38:39], v[38:39]
	s_nop 0
	v_add_f32_e32 v40, v41, v40
	s_nop 1
	v_mov_b32_dpp v41, v40 quad_perm:[1,0,3,2] row_mask:0xf bank_mask:0xf
	s_waitcnt lgkmcnt(0)
	v_add_f32_e32 v40, v40, v41
	s_nop 1
	v_mov_b32_dpp v41, v40 quad_perm:[2,3,0,1] row_mask:0xf bank_mask:0xf
	s_waitcnt lgkmcnt(0)
	v_add_f32_e32 v40, v40, v41
	s_nop 1
	v_mov_b32_dpp v41, v40 row_half_mirror row_mask:0xf bank_mask:0xf
	s_waitcnt lgkmcnt(0)
	v_add_f32_e32 v40, v40, v41
	s_nop 1
	v_mov_b32_dpp v41, v40 row_mirror row_mask:0xf bank_mask:0xf
	s_waitcnt lgkmcnt(0)
	v_add_f32_e32 v40, v40, v41
	v_mov_b32_e32 v41, v40
	v_mov_b32_e32 v89, v40
	s_nop 1
	v_permlane16_swap_b32_e32 v41, v89
	s_nop 1
	v_mov_b32_dpp v41, v89 quad_perm:[0,1,2,3] row_mask:0x5 bank_mask:0xf
	s_waitcnt lgkmcnt(0)
	v_add_f32_e32 v40, v40, v41
	v_mov_b32_e32 v41, v40
	v_mov_b32_e32 v89, v40
	s_nop 1
	v_permlane32_swap_b32_e32 v41, v89
	s_nop 1
	v_mov_b32_dpp v41, v89 quad_perm:[0,1,2,3] row_mask:0x3 bank_mask:0xf
	s_waitcnt lgkmcnt(0)
	v_add_f32_e32 v40, v40, v41
	v_add_f32_e32 v40, 0x358637bd, v40
	v_rsq_f32_e32 v40, v40
	s_nop 0
	v_mul_f32_e32 v40, 0x3db504f3, v40
	v_pk_mul_f32 v[38:39], v[38:39], v[40:41] op_sel_hi:[1,0]
	v_lshlrev_b32_e32 v40, 16, v70
	v_cvt_pk_bf16_f32 v38, v38, v39
	v_add_u32_e32 v39, 0x400, v48
	ds_write2_b32 v39, v42, v38 offset0:16 offset1:84
	v_lshlrev_b32_e32 v42, 16, v68
	v_and_b32_e32 v41, 0xffff0000, v70
	s_waitcnt vmcnt(7)
	v_pk_fma_f32 v[42:43], v[10:11], v[42:43], 0 op_sel_hi:[1,1,0]
	v_lshlrev_b32_e32 v38, 16, v69
	v_and_b32_e32 v39, 0xffff0000, v69
	s_waitcnt vmcnt(6)
	v_pk_fma_f32 v[42:43], v[12:13], v[40:41], v[42:43]
	v_pk_fma_f32 v[40:41], v[10:11], v[40:41], 0 op_sel_hi:[1,1,0]
	s_waitcnt vmcnt(5)
	v_pk_fma_f32 v[42:43], v[14:15], v[38:39], v[42:43]
	v_pk_fma_f32 v[40:41], v[12:13], v[38:39], v[40:41]
	s_waitcnt vmcnt(4)
	v_pk_fma_f32 v[42:43], v[16:17], v[36:37], v[42:43]
	v_pk_fma_f32 v[40:41], v[14:15], v[36:37], v[40:41]
	v_mul_f32_e32 v44, 0xbfb8aa3b, v43
	v_exp_f32_e32 v44, v44
	ds_write_b32 v48, v18 offset:1632
	v_pk_fma_f32 v[40:41], v[16:17], v[34:35], v[40:41]
	v_pk_fma_f32 v[38:39], v[10:11], v[38:39], 0 op_sel_hi:[1,1,0]
	v_add_f32_e32 v44, 1.0, v44
	v_rcp_f32_e32 v45, v44
	v_mul_f32_e32 v44, 0xbfb8aa3b, v42
	v_exp_f32_e32 v44, v44
	v_pk_fma_f32 v[38:39], v[12:13], v[36:37], v[38:39]
	v_pk_fma_f32 v[36:37], v[10:11], v[36:37], 0 op_sel_hi:[1,1,0]
	v_pk_fma_f32 v[38:39], v[14:15], v[34:35], v[38:39]
	v_add_f32_e32 v44, 1.0, v44
	v_rcp_f32_e32 v44, v44
	v_pk_fma_f32 v[38:39], v[16:17], v[32:33], v[38:39]
	v_pk_fma_f32 v[36:37], v[12:13], v[34:35], v[36:37]
	v_pk_fma_f32 v[34:35], v[10:11], v[34:35], 0 op_sel_hi:[1,1,0]
	v_pk_mul_f32 v[42:43], v[42:43], v[44:45]
	v_pk_fma_f32 v[36:37], v[14:15], v[32:33], v[36:37]
	v_pk_mul_f32 v[44:45], v[42:43], v[42:43]
	v_pk_fma_f32 v[36:37], v[16:17], v[30:31], v[36:37]
	v_add_f32_e32 v44, v45, v44
	s_nop 1
	v_mov_b32_dpp v45, v44 quad_perm:[1,0,3,2] row_mask:0xf bank_mask:0xf
	v_pk_fma_f32 v[34:35], v[12:13], v[32:33], v[34:35]
	v_lshlrev_b32_e32 v18, 16, v76
	v_pk_fma_f32 v[34:35], v[14:15], v[30:31], v[34:35]
	v_pk_fma_f32 v[32:33], v[10:11], v[32:33], 0 op_sel_hi:[1,1,0]
	s_waitcnt lgkmcnt(0)
	v_add_f32_e32 v44, v44, v45
	s_nop 1
	v_mov_b32_dpp v45, v44 quad_perm:[2,3,0,1] row_mask:0xf bank_mask:0xf
	v_pk_fma_f32 v[34:35], v[16:17], v[18:19], v[34:35]
	v_pk_fma_f32 v[32:33], v[12:13], v[30:31], v[32:33]
	v_pk_fma_f32 v[30:31], v[10:11], v[30:31], 0 op_sel_hi:[1,1,0]
	v_pk_fma_f32 v[32:33], v[14:15], v[18:19], v[32:33]
	s_waitcnt lgkmcnt(0)
	v_add_f32_e32 v44, v44, v45
	s_nop 1
	v_mov_b32_dpp v45, v44 row_half_mirror row_mask:0xf bank_mask:0xf
	v_pk_fma_f32 v[32:33], v[16:17], v[20:21], v[32:33]
	v_pk_fma_f32 v[30:31], v[12:13], v[18:19], v[30:31]
	v_pk_fma_f32 v[10:11], v[10:11], v[18:19], 0 op_sel_hi:[1,1,0]
	v_pk_fma_f32 v[30:31], v[14:15], v[20:21], v[30:31]
	s_waitcnt lgkmcnt(0)
	v_add_f32_e32 v44, v44, v45
	s_nop 1
	v_mov_b32_dpp v45, v44 row_mirror row_mask:0xf bank_mask:0xf
	v_pk_fma_f32 v[30:31], v[16:17], v[22:23], v[30:31]
	v_pk_fma_f32 v[10:11], v[12:13], v[20:21], v[10:11]
	v_lshlrev_b32_e32 v20, 16, v54
	v_pk_fma_f32 v[10:11], v[14:15], v[22:23], v[10:11]
	s_waitcnt lgkmcnt(0)
	v_add_f32_e32 v44, v44, v45
	v_mov_b32_e32 v45, v44
	v_mov_b32_e32 v89, v44
	s_nop 1
	v_permlane16_swap_b32_e32 v45, v89
	s_nop 1
	v_mov_b32_dpp v45, v89 quad_perm:[0,1,2,3] row_mask:0x5 bank_mask:0xf
	v_pk_fma_f32 v[10:11], v[16:17], v[24:25], v[10:11]
	v_lshlrev_b32_e32 v22, 16, v51
	v_mul_f32_e32 v12, 0xbfb8aa3b, v11
	v_exp_f32_e32 v12, v12
	s_waitcnt lgkmcnt(0)
; #define LAS __attribute__((address_space(3)))
; DI unsigned pk2(float lo, float hi) { f32x2 v = {lo, hi}; bf16x2_t b = __builtin_convertvector(v, bf16x2_t); return __builtin_bit_cast(unsigned, b); }
; DI float siluf_(float x) { return x * __builtin_amdgcn_rcpf(1.f + __expf(-x)); }
; DI void gdn_prep_item(LAS unsigned char* lds, const Ctx& c, int l, int item) {
;     ...
;             for (int t = 0; t < 8; ++t) {
;                 float a0 = 0.f, a1 = 0.f;
; #pragma unroll
;                 for (int j = 0; j < 4; ++j) { a0 += w0[j] * x0[t + j]; a1 += w1[j] * x1[t + j]; }
;                 a0 = siluf_(a0); a1 = siluf_(a1);
;                 const int tl = 8 * tg + t;
;                 if (which < 2) {
;                     const float ss = wave_sum(a0 * a0 + a1 * a1); float rs = __builtin_amdgcn_rsqf(ss + RMS_EPS); if (which == 0) rs *= 0.08838834764831845f;
;                     a0 *= rs; a1 *= rs;
;                     *(LAS unsigned*)(lds + (which == 0 ? GP_QB : GP_KB) + tl * 272 + cp * 4) = pk2(a0, a1);
;                     if (which == 1) { kf[tl * 129 + 2 * cp] = a0; kf[tl * 129 + 2 * cp + 1] = a1; }
;                 } else { vf[tl * 129 + 2 * cp] = a0; vf[tl * 129 + 2 * cp + 1] = a1; }
	v_add_f32_e32 v44, v44, v45
	v_mov_b32_e32 v45, v44
	v_mov_b32_e32 v89, v44
	s_nop 1
	v_permlane32_swap_b32_e32 v45, v89
	s_nop 1
	v_mov_b32_dpp v45, v89 quad_perm:[0,1,2,3] row_mask:0x3 bank_mask:0xf
	v_and_b32_e32 v23, 0xffff0000, v51
	v_add_f32_e32 v12, 1.0, v12
	v_rcp_f32_e32 v13, v12
	v_mul_f32_e32 v12, 0xbfb8aa3b, v10
	s_waitcnt lgkmcnt(0)
	v_add_f32_e32 v44, v44, v45
	v_add_f32_e32 v44, 0x358637bd, v44
	v_rsq_f32_e32 v44, v44
	v_exp_f32_e32 v12, v12
	v_lshlrev_b32_e32 v24, 16, v53
	v_and_b32_e32 v25, 0xffff0000, v53
	v_pk_mul_f32 v[42:43], v[42:43], v[44:45] op_sel_hi:[1,0]
	v_add_f32_e32 v12, 1.0, v12
	v_cvt_pk_bf16_f32 v44, v42, v43
	ds_write_b32 v79, v44 offset:17408
	ds_write_b64 v46, v[42:43] offset:34816
	v_add_u32_e32 v42, s4, v67
	v_add_u32_e32 v44, 0x8800, v42
	v_mul_f32_e32 v42, 0xbfb8aa3b, v41
	v_exp_f32_e32 v42, v42
	v_rcp_f32_e32 v12, v12
	v_and_b32_e32 v21, 0xffff0000, v54
	v_lshlrev_b32_e32 v18, 16, v57
	v_add_f32_e32 v42, 1.0, v42
	v_rcp_f32_e32 v43, v42
	v_mul_f32_e32 v42, 0xbfb8aa3b, v40
	v_exp_f32_e32 v42, v42
	v_pk_mul_f32 v[10:11], v[10:11], v[12:13]
	v_and_b32_e32 v19, 0xffff0000, v57
	v_pk_mul_f32 v[12:13], v[10:11], v[10:11]
	v_add_f32_e32 v42, 1.0, v42
	v_rcp_f32_e32 v42, v42
	v_add_f32_e32 v12, v13, v12
	s_nop 1
	v_mov_b32_dpp v13, v12 quad_perm:[1,0,3,2] row_mask:0xf bank_mask:0xf
	v_lshlrev_b32_e32 v14, 16, v58
	v_pk_mul_f32 v[40:41], v[40:41], v[42:43]
	v_and_b32_e32 v15, 0xffff0000, v58
	v_pk_mul_f32 v[42:43], v[40:41], v[40:41]
	s_waitcnt lgkmcnt(0)
	v_add_f32_e32 v12, v12, v13
	v_add_f32_e32 v42, v43, v42
	s_nop 1
	v_mov_b32_dpp v43, v42 quad_perm:[1,0,3,2] row_mask:0xf bank_mask:0xf
	s_nop 1
	v_mov_b32_dpp v13, v12 quad_perm:[2,3,0,1] row_mask:0xf bank_mask:0xf
	v_lshlrev_b32_e32 v16, 16, v60
	v_and_b32_e32 v17, 0xffff0000, v60
	s_waitcnt lgkmcnt(0)
	v_add_f32_e32 v42, v42, v43
	s_nop 1
	v_mov_b32_dpp v43, v42 quad_perm:[2,3,0,1] row_mask:0xf bank_mask:0xf
	s_waitcnt lgkmcnt(0)
	v_add_f32_e32 v12, v12, v13
	s_nop 1
	v_mov_b32_dpp v13, v12 row_half_mirror row_mask:0xf bank_mask:0xf
	s_waitcnt lgkmcnt(0)
	v_add_f32_e32 v42, v42, v43
	s_nop 1
	v_mov_b32_dpp v43, v42 row_half_mirror row_mask:0xf bank_mask:0xf
	s_waitcnt lgkmcnt(0)
	v_add_f32_e32 v12, v12, v13
	s_nop 1
	v_mov_b32_dpp v13, v12 row_mirror row_mask:0xf bank_mask:0xf
	s_waitcnt lgkmcnt(0)
	v_add_f32_e32 v42, v42, v43
	s_nop 1
	v_mov_b32_dpp v43, v42 row_mirror row_mask:0xf bank_mask:0xf
	s_waitcnt lgkmcnt(0)
	v_add_f32_e32 v12, v12, v13
	v_mov_b32_e32 v13, v12
	v_mov_b32_e32 v89, v12
	s_nop 1
	v_permlane16_swap_b32_e32 v13, v89
	s_nop 1
	v_mov_b32_dpp v13, v89 quad_perm:[0,1,2,3] row_mask:0x5 bank_mask:0xf
	s_waitcnt lgkmcnt(0)
	v_add_f32_e32 v42, v42, v43
	v_mov_b32_e32 v43, v42
	v_mov_b32_e32 v89, v42
	s_nop 1
	v_permlane16_swap_b32_e32 v43, v89
	s_nop 1
	v_mov_b32_dpp v43, v89 quad_perm:[0,1,2,3] row_mask:0x5 bank_mask:0xf
	s_waitcnt lgkmcnt(0)
	v_add_f32_e32 v12, v12, v13
	v_mov_b32_e32 v13, v12
	v_mov_b32_e32 v89, v12
	s_nop 1
	v_permlane32_swap_b32_e32 v13, v89
	s_nop 1
	v_mov_b32_dpp v13, v89 quad_perm:[0,1,2,3] row_mask:0x3 bank_mask:0xf
	s_waitcnt lgkmcnt(0)
	v_add_f32_e32 v42, v42, v43
	v_mov_b32_e32 v43, v42
	v_mov_b32_e32 v89, v42
	s_nop 1
	v_permlane32_swap_b32_e32 v43, v89
	s_nop 1
	v_mov_b32_dpp v43, v89 quad_perm:[0,1,2,3] row_mask:0x3 bank_mask:0xf
	s_waitcnt lgkmcnt(0)
	v_add_f32_e32 v12, v12, v13
	v_add_f32_e32 v12, 0x358637bd, v12
	v_rsq_f32_e32 v12, v12
	s_waitcnt lgkmcnt(0)
	v_add_f32_e32 v42, v42, v43
	v_add_f32_e32 v42, 0x358637bd, v42
	v_rsq_f32_e32 v42, v42
	v_pk_mul_f32 v[10:11], v[10:11], v[12:13] op_sel_hi:[1,0]
	v_and_b32_e32 v13, 0xffff0000, v59
	v_cvt_pk_bf16_f32 v12, v10, v11
	v_pk_mul_f32 v[40:41], v[40:41], v[42:43] op_sel_hi:[1,0]
	ds_write2_b32 v44, v40, v41 offset1:1
	v_cvt_pk_bf16_f32 v42, v40, v41
	v_mul_f32_e32 v40, 0xbfb8aa3b, v39
	v_exp_f32_e32 v40, v40
	v_add_u32_e32 v43, s5, v67
	v_add_f32_e32 v40, 1.0, v40
	v_rcp_f32_e32 v41, v40
	v_mul_f32_e32 v40, 0xbfb8aa3b, v38
	v_exp_f32_e32 v40, v40
	s_nop 0
	v_add_f32_e32 v40, 1.0, v40
	v_rcp_f32_e32 v40, v40
	s_nop 0
	v_pk_mul_f32 v[38:39], v[38:39], v[40:41]
	s_nop 0
	v_pk_mul_f32 v[40:41], v[38:39], v[38:39]
	s_nop 0
	v_add_f32_e32 v40, v41, v40
	s_nop 1
	v_mov_b32_dpp v41, v40 quad_perm:[1,0,3,2] row_mask:0xf bank_mask:0xf
	s_waitcnt lgkmcnt(0)
	v_add_f32_e32 v40, v40, v41
	s_nop 1
	v_mov_b32_dpp v41, v40 quad_perm:[2,3,0,1] row_mask:0xf bank_mask:0xf
	s_waitcnt lgkmcnt(0)
	v_add_f32_e32 v40, v40, v41
	s_nop 1
	v_mov_b32_dpp v41, v40 row_half_mirror row_mask:0xf bank_mask:0xf
	s_waitcnt lgkmcnt(0)
	v_add_f32_e32 v40, v40, v41
	s_nop 1
	v_mov_b32_dpp v41, v40 row_mirror row_mask:0xf bank_mask:0xf
	s_waitcnt lgkmcnt(0)
	v_add_f32_e32 v40, v40, v41
	v_mov_b32_e32 v41, v40
	v_mov_b32_e32 v89, v40
	s_nop 1
	v_permlane16_swap_b32_e32 v41, v89
	s_nop 1
	v_mov_b32_dpp v41, v89 quad_perm:[0,1,2,3] row_mask:0x5 bank_mask:0xf
	s_waitcnt lgkmcnt(0)
	v_add_f32_e32 v40, v40, v41
	v_mov_b32_e32 v41, v40
	v_mov_b32_e32 v89, v40
	s_nop 1
	v_permlane32_swap_b32_e32 v41, v89
	s_nop 1
	v_mov_b32_dpp v41, v89 quad_perm:[0,1,2,3] row_mask:0x3 bank_mask:0xf
	s_waitcnt lgkmcnt(0)
	v_add_f32_e32 v40, v40, v41
	v_add_f32_e32 v40, 0x358637bd, v40
	v_rsq_f32_e32 v40, v40
	s_nop 0
	v_pk_mul_f32 v[38:39], v[38:39], v[40:41] op_sel_hi:[1,0]
	s_nop 0
	v_cvt_pk_bf16_f32 v40, v38, v39
	v_add_u32_e32 v41, 0x4400, v48
	ds_write2_b32 v41, v42, v40 offset1:68
	ds_write_b64 v43, v[38:39] offset:34816
	v_add_u32_e32 v38, s6, v67
	v_add_u32_e32 v40, 0x8800, v38
	v_mul_f32_e32 v38, 0xbfb8aa3b, v37
	v_exp_f32_e32 v38, v38
	s_nop 0
	v_add_f32_e32 v38, 1.0, v38
	v_rcp_f32_e32 v39, v38
	v_mul_f32_e32 v38, 0xbfb8aa3b, v36
	v_exp_f32_e32 v38, v38
	s_nop 0
	v_add_f32_e32 v38, 1.0, v38
	v_rcp_f32_e32 v38, v38
	s_nop 0
	v_pk_mul_f32 v[36:37], v[36:37], v[38:39]
	s_nop 0
	v_pk_mul_f32 v[38:39], v[36:37], v[36:37]
	s_nop 0
	v_add_f32_e32 v38, v39, v38
	s_nop 1
	v_mov_b32_dpp v39, v38 quad_perm:[1,0,3,2] row_mask:0xf bank_mask:0xf
	s_waitcnt lgkmcnt(0)
; #define LAS __attribute__((address_space(3)))
; DI unsigned pk2(float lo, float hi) { f32x2 v = {lo, hi}; bf16x2_t b = __builtin_convertvector(v, bf16x2_t); return __builtin_bit_cast(unsigned, b); }
; DI float siluf_(float x) { return x * __builtin_amdgcn_rcpf(1.f + __expf(-x)); }
; DI void gdn_prep_item(LAS unsigned char* lds, const Ctx& c, int l, int item) {
;     ...
;             for (int t = 0; t < 8; ++t) {
;                 float a0 = 0.f, a1 = 0.f;
; #pragma unroll
;                 for (int j = 0; j < 4; ++j) { a0 += w0[j] * x0[t + j]; a1 += w1[j] * x1[t + j]; }
;                 a0 = siluf_(a0); a1 = siluf_(a1);
;                 const int tl = 8 * tg + t;
;                 if (which < 2) {
;                     const float ss = wave_sum(a0 * a0 + a1 * a1); float rs = __builtin_amdgcn_rsqf(ss + RMS_EPS); if (which == 0) rs *= 0.08838834764831845f;
;                     a0 *= rs; a1 *= rs;
;                     *(LAS unsigned*)(lds + (which == 0 ? GP_QB : GP_KB) + tl * 272 + cp * 4) = pk2(a0, a1);
;                     if (which == 1) { kf[tl * 129 + 2 * cp] = a0; kf[tl * 129 + 2 * cp + 1] = a1; }
;                 } else { vf[tl * 129 + 2 * cp] = a0; vf[tl * 129 + 2 * cp + 1] = a1; }
	v_add_f32_e32 v38, v38, v39
	s_nop 1
	v_mov_b32_dpp v39, v38 quad_perm:[2,3,0,1] row_mask:0xf bank_mask:0xf
	s_waitcnt lgkmcnt(0)
	v_add_f32_e32 v38, v38, v39
	s_nop 1
	v_mov_b32_dpp v39, v38 row_half_mirror row_mask:0xf bank_mask:0xf
	s_waitcnt lgkmcnt(0)
	v_add_f32_e32 v38, v38, v39
	s_nop 1
	v_mov_b32_dpp v39, v38 row_mirror row_mask:0xf bank_mask:0xf
	s_waitcnt lgkmcnt(0)
	v_add_f32_e32 v38, v38, v39
	v_mov_b32_e32 v39, v38
	v_mov_b32_e32 v89, v38
	s_nop 1
	v_permlane16_swap_b32_e32 v39, v89
	s_nop 1
	v_mov_b32_dpp v39, v89 quad_perm:[0,1,2,3] row_mask:0x5 bank_mask:0xf
	s_waitcnt lgkmcnt(0)
	v_add_f32_e32 v38, v38, v39
	v_mov_b32_e32 v39, v38
	v_mov_b32_e32 v89, v38
	s_nop 1
	v_permlane32_swap_b32_e32 v39, v89
	s_nop 1
	v_mov_b32_dpp v39, v89 quad_perm:[0,1,2,3] row_mask:0x3 bank_mask:0xf
	s_waitcnt lgkmcnt(0)
	v_add_f32_e32 v38, v38, v39
	v_add_f32_e32 v38, 0x358637bd, v38
	v_rsq_f32_e32 v38, v38
	s_nop 0
	v_pk_mul_f32 v[36:37], v[36:37], v[38:39] op_sel_hi:[1,0]
	s_nop 0
	v_cvt_pk_bf16_f32 v38, v36, v37
	ds_write2_b32 v40, v36, v37 offset1:1
	v_mul_f32_e32 v36, 0xbfb8aa3b, v35
	v_exp_f32_e32 v36, v36
	v_add_u32_e32 v39, s7, v67
	v_add_f32_e32 v36, 1.0, v36
	v_rcp_f32_e32 v37, v36
	v_mul_f32_e32 v36, 0xbfb8aa3b, v34
	v_exp_f32_e32 v36, v36
	s_nop 0
	v_add_f32_e32 v36, 1.0, v36
	v_rcp_f32_e32 v36, v36
	s_nop 0
	v_pk_mul_f32 v[34:35], v[34:35], v[36:37]
	s_nop 0
	v_pk_mul_f32 v[36:37], v[34:35], v[34:35]
	s_nop 0
	v_add_f32_e32 v36, v37, v36
	s_nop 1
	v_mov_b32_dpp v37, v36 quad_perm:[1,0,3,2] row_mask:0xf bank_mask:0xf
	s_waitcnt lgkmcnt(0)
	v_add_f32_e32 v36, v36, v37
	s_nop 1
	v_mov_b32_dpp v37, v36 quad_perm:[2,3,0,1] row_mask:0xf bank_mask:0xf
	s_waitcnt lgkmcnt(0)
	v_add_f32_e32 v36, v36, v37
	s_nop 1
	v_mov_b32_dpp v37, v36 row_half_mirror row_mask:0xf bank_mask:0xf
	s_waitcnt lgkmcnt(0)
	v_add_f32_e32 v36, v36, v37
	s_nop 1
	v_mov_b32_dpp v37, v36 row_mirror row_mask:0xf bank_mask:0xf
	s_waitcnt lgkmcnt(0)
	v_add_f32_e32 v36, v36, v37
	v_mov_b32_e32 v37, v36
	v_mov_b32_e32 v89, v36
	s_nop 1
	v_permlane16_swap_b32_e32 v37, v89
	s_nop 1
	v_mov_b32_dpp v37, v89 quad_perm:[0,1,2,3] row_mask:0x5 bank_mask:0xf
	s_waitcnt lgkmcnt(0)
	v_add_f32_e32 v36, v36, v37
	v_mov_b32_e32 v37, v36
	v_mov_b32_e32 v89, v36
	s_nop 1
	v_permlane32_swap_b32_e32 v37, v89
	s_nop 1
	v_mov_b32_dpp v37, v89 quad_perm:[0,1,2,3] row_mask:0x3 bank_mask:0xf
	s_waitcnt lgkmcnt(0)
	v_add_f32_e32 v36, v36, v37
	v_add_f32_e32 v36, 0x358637bd, v36
	v_rsq_f32_e32 v36, v36
	s_nop 0
	v_pk_mul_f32 v[34:35], v[34:35], v[36:37] op_sel_hi:[1,0]
	s_nop 0
	v_cvt_pk_bf16_f32 v36, v34, v35
	ds_write2_b32 v41, v38, v36 offset0:136 offset1:204
	ds_write_b64 v39, v[34:35] offset:34816
	v_add_u32_e32 v34, s9, v67
	v_add_u32_e32 v36, 0x8800, v34
	v_mul_f32_e32 v34, 0xbfb8aa3b, v33
	v_exp_f32_e32 v34, v34
	v_add_u32_e32 v38, s83, v0
	v_add_f32_e32 v34, 1.0, v34
	v_rcp_f32_e32 v35, v34
	v_mul_f32_e32 v34, 0xbfb8aa3b, v32
	v_exp_f32_e32 v34, v34
	s_nop 0
	v_add_f32_e32 v34, 1.0, v34
	v_rcp_f32_e32 v34, v34
	s_nop 0
	v_pk_mul_f32 v[32:33], v[32:33], v[34:35]
	s_nop 0
	v_pk_mul_f32 v[34:35], v[32:33], v[32:33]
	s_nop 0
	v_add_f32_e32 v34, v35, v34
	s_nop 1
	v_mov_b32_dpp v35, v34 quad_perm:[1,0,3,2] row_mask:0xf bank_mask:0xf
	s_waitcnt lgkmcnt(0)
	v_add_f32_e32 v34, v34, v35
	s_nop 1
	v_mov_b32_dpp v35, v34 quad_perm:[2,3,0,1] row_mask:0xf bank_mask:0xf
	s_waitcnt lgkmcnt(0)
	v_add_f32_e32 v34, v34, v35
	s_nop 1
	v_mov_b32_dpp v35, v34 row_half_mirror row_mask:0xf bank_mask:0xf
	s_waitcnt lgkmcnt(0)
	v_add_f32_e32 v34, v34, v35
	s_nop 1
	v_mov_b32_dpp v35, v34 row_mirror row_mask:0xf bank_mask:0xf
	s_waitcnt lgkmcnt(0)
	v_add_f32_e32 v34, v34, v35
	v_mov_b32_e32 v35, v34
	v_mov_b32_e32 v89, v34
	s_nop 1
	v_permlane16_swap_b32_e32 v35, v89
	s_nop 1
	v_mov_b32_dpp v35, v89 quad_perm:[0,1,2,3] row_mask:0x5 bank_mask:0xf
	s_waitcnt lgkmcnt(0)
	v_add_f32_e32 v34, v34, v35
	v_mov_b32_e32 v35, v34
	v_mov_b32_e32 v89, v34
	s_nop 1
	v_permlane32_swap_b32_e32 v35, v89
	s_nop 1
	v_mov_b32_dpp v35, v89 quad_perm:[0,1,2,3] row_mask:0x3 bank_mask:0xf
	s_waitcnt lgkmcnt(0)
	v_add_f32_e32 v34, v34, v35
	v_add_f32_e32 v34, 0x358637bd, v34
	v_rsq_f32_e32 v34, v34
	s_nop 0
	v_pk_mul_f32 v[32:33], v[32:33], v[34:35] op_sel_hi:[1,0]
	s_nop 0
	v_cvt_pk_bf16_f32 v34, v32, v33
	ds_write2_b32 v36, v32, v33 offset1:1
	v_mul_f32_e32 v32, 0xbfb8aa3b, v31
	v_exp_f32_e32 v32, v32
	v_add_u32_e32 v35, s11, v67
	v_add_f32_e32 v32, 1.0, v32
	v_rcp_f32_e32 v33, v32
	v_mul_f32_e32 v32, 0xbfb8aa3b, v30
	v_exp_f32_e32 v32, v32
	s_nop 0
	v_add_f32_e32 v32, 1.0, v32
	v_rcp_f32_e32 v32, v32
	s_nop 0
	v_pk_mul_f32 v[30:31], v[30:31], v[32:33]
	s_nop 0
	v_pk_mul_f32 v[32:33], v[30:31], v[30:31]
	s_nop 0
	v_add_f32_e32 v32, v33, v32
	s_nop 1
	v_mov_b32_dpp v33, v32 quad_perm:[1,0,3,2] row_mask:0xf bank_mask:0xf
	s_waitcnt lgkmcnt(0)
	v_add_f32_e32 v32, v32, v33
	s_nop 1
	v_mov_b32_dpp v33, v32 quad_perm:[2,3,0,1] row_mask:0xf bank_mask:0xf
	s_waitcnt lgkmcnt(0)
	v_add_f32_e32 v32, v32, v33
	s_nop 1
	v_mov_b32_dpp v33, v32 row_half_mirror row_mask:0xf bank_mask:0xf
	s_waitcnt lgkmcnt(0)
	v_add_f32_e32 v32, v32, v33
	s_nop 1
	v_mov_b32_dpp v33, v32 row_mirror row_mask:0xf bank_mask:0xf
	s_waitcnt lgkmcnt(0)
	v_add_f32_e32 v32, v32, v33
	v_mov_b32_e32 v33, v32
	v_mov_b32_e32 v89, v32
	s_nop 1
	v_permlane16_swap_b32_e32 v33, v89
	s_nop 1
	v_mov_b32_dpp v33, v89 quad_perm:[0,1,2,3] row_mask:0x5 bank_mask:0xf
	s_waitcnt lgkmcnt(0)
	v_add_f32_e32 v32, v32, v33
	v_mov_b32_e32 v33, v32
	v_mov_b32_e32 v89, v32
	s_nop 1
	v_permlane32_swap_b32_e32 v33, v89
	s_nop 1
	v_mov_b32_dpp v33, v89 quad_perm:[0,1,2,3] row_mask:0x3 bank_mask:0xf
	s_waitcnt lgkmcnt(0)
; #define LAS __attribute__((address_space(3)))
; DI unsigned pk2(float lo, float hi) { f32x2 v = {lo, hi}; bf16x2_t b = __builtin_convertvector(v, bf16x2_t); return __builtin_bit_cast(unsigned, b); }
; DI float siluf_(float x) { return x * __builtin_amdgcn_rcpf(1.f + __expf(-x)); }
; #define BLOCK_SYNC() __syncthreads()
; DI void gdn_prep_item(LAS unsigned char* lds, const Ctx& c, int l, int item) {
;     ...
;             for (int t = 0; t < 8; ++t) {
;                 float a0 = 0.f, a1 = 0.f;
; #pragma unroll
;                 for (int j = 0; j < 4; ++j) { a0 += w0[j] * x0[t + j]; a1 += w1[j] * x1[t + j]; }
;                 a0 = siluf_(a0); a1 = siluf_(a1);
;                 const int tl = 8 * tg + t;
;                 if (which < 2) {
;                     const float ss = wave_sum(a0 * a0 + a1 * a1); float rs = __builtin_amdgcn_rsqf(ss + RMS_EPS); if (which == 0) rs *= 0.08838834764831845f;
;                     a0 *= rs; a1 *= rs;
;                     *(LAS unsigned*)(lds + (which == 0 ? GP_QB : GP_KB) + tl * 272 + cp * 4) = pk2(a0, a1);
;                     if (which == 1) { kf[tl * 129 + 2 * cp] = a0; kf[tl * 129 + 2 * cp + 1] = a1; }
;                 } else { vf[tl * 129 + 2 * cp] = a0; vf[tl * 129 + 2 * cp + 1] = a1; }
;             }
;         }
;     }
;     BLOCK_SYNC();
;     {
;         const int mat = wave >> 2, rb = wave & 3, m16 = lane & 15, g4 = lane >> 4;
;         const LAS unsigned char* Ab = lds + (mat == 0 ? GP_KB : GP_QB) + (16 * rb + m16) * 272 + g4 * 16;
	v_add_f32_e32 v32, v32, v33
	v_add_f32_e32 v32, 0x358637bd, v32
	v_rsq_f32_e32 v32, v32
	s_nop 0
	v_pk_mul_f32 v[30:31], v[30:31], v[32:33] op_sel_hi:[1,0]
	s_nop 0
	v_cvt_pk_bf16_f32 v32, v30, v31
	v_add_u32_e32 v33, 0x4800, v48
	ds_write2_b32 v33, v34, v32 offset0:16 offset1:84
	ds_write_b64 v35, v[30:31] offset:34816
	v_and_b32_e32 v35, 0xffff0000, v50
	v_lshlrev_b32_e32 v34, 16, v50
	v_add_u32_e32 v30, s14, v67
	s_waitcnt vmcnt(3)
	v_pk_fma_f32 v[34:35], v[2:3], v[34:35], 0 op_sel_hi:[1,1,0]
	v_add_u32_e32 v30, 0x8800, v30
	s_waitcnt vmcnt(2)
	v_pk_fma_f32 v[34:35], v[4:5], v[22:23], v[34:35]
	ds_write_b32 v48, v12 offset:19040
	ds_write2_b32 v30, v10, v11 offset1:1
	v_lshlrev_b32_e32 v30, 16, v52
	v_and_b32_e32 v31, 0xffff0000, v52
	s_waitcnt vmcnt(1)
	v_pk_fma_f32 v[34:35], v[6:7], v[24:25], v[34:35]
	v_pk_fma_f32 v[22:23], v[2:3], v[22:23], 0 op_sel_hi:[1,1,0]
	s_waitcnt vmcnt(0)
	v_pk_fma_f32 v[34:35], v[8:9], v[30:31], v[34:35]
	v_pk_fma_f32 v[22:23], v[4:5], v[24:25], v[22:23]
	v_mul_f32_e32 v36, 0xbfb8aa3b, v35
	v_exp_f32_e32 v36, v36
	v_lshlrev_b32_e32 v32, 16, v55
	v_and_b32_e32 v33, 0xffff0000, v55
	v_pk_fma_f32 v[22:23], v[6:7], v[30:31], v[22:23]
	v_add_f32_e32 v36, 1.0, v36
	v_rcp_f32_e32 v37, v36
	v_mul_f32_e32 v36, 0xbfb8aa3b, v34
	v_exp_f32_e32 v36, v36
	v_pk_fma_f32 v[22:23], v[8:9], v[32:33], v[22:23]
	v_lshlrev_b32_e32 v10, 16, v56
	v_and_b32_e32 v11, 0xffff0000, v56
	v_add_f32_e32 v36, 1.0, v36
	v_rcp_f32_e32 v36, v36
	v_lshlrev_b32_e32 v12, 16, v59
	v_pk_mul_f32 v[34:35], v[34:35], v[36:37]
	ds_write_b64 v38, v[34:35]
	v_mul_f32_e32 v34, 0xbfb8aa3b, v23
	v_exp_f32_e32 v34, v34
	v_add_u32_e32 v36, s4, v0
	v_and_b32_e32 v38, 15, v26
	v_mov_b32_e32 v54, v38
	v_add_f32_e32 v34, 1.0, v34
	v_rcp_f32_e32 v35, v34
	v_mul_f32_e32 v34, 0xbfb8aa3b, v22
	v_exp_f32_e32 v34, v34
	s_nop 0
	v_add_f32_e32 v34, 1.0, v34
	v_rcp_f32_e32 v34, v34
	s_nop 0
	v_pk_mul_f32 v[22:23], v[22:23], v[34:35]
	ds_write2_b32 v36, v22, v23 offset1:1
	v_pk_fma_f32 v[22:23], v[2:3], v[24:25], 0 op_sel_hi:[1,1,0]
	v_add_u32_e32 v34, s5, v0
	v_pk_fma_f32 v[22:23], v[4:5], v[30:31], v[22:23]
	s_cselect_b64 s[4:5], -1, 0
	v_pk_fma_f32 v[22:23], v[6:7], v[32:33], v[22:23]
	s_cmpk_lt_u32 s82, 0x100
	v_pk_fma_f32 v[22:23], v[8:9], v[20:21], v[22:23]
	s_nop 0
	v_mul_f32_e32 v24, 0xbfb8aa3b, v23
	v_exp_f32_e32 v24, v24
	s_nop 0
	v_add_f32_e32 v24, 1.0, v24
	v_rcp_f32_e32 v25, v24
	v_mul_f32_e32 v24, 0xbfb8aa3b, v22
	v_exp_f32_e32 v24, v24
	s_nop 0
	v_add_f32_e32 v24, 1.0, v24
	v_rcp_f32_e32 v24, v24
	s_nop 0
	v_pk_mul_f32 v[22:23], v[22:23], v[24:25]
	ds_write_b64 v34, v[22:23]
	v_pk_fma_f32 v[22:23], v[2:3], v[30:31], 0 op_sel_hi:[1,1,0]
	v_add_u32_e32 v34, s6, v0
	v_pk_fma_f32 v[22:23], v[4:5], v[32:33], v[22:23]
	v_add_u32_e32 v30, s7, v0
	v_pk_fma_f32 v[22:23], v[6:7], v[20:21], v[22:23]
	s_cselect_b64 s[6:7], -1, 0
	v_pk_fma_f32 v[22:23], v[8:9], v[18:19], v[22:23]
	s_nop 0
	v_mul_f32_e32 v24, 0xbfb8aa3b, v23
	v_exp_f32_e32 v24, v24
	s_nop 0
	v_add_f32_e32 v24, 1.0, v24
	v_rcp_f32_e32 v25, v24
	v_mul_f32_e32 v24, 0xbfb8aa3b, v22
	v_exp_f32_e32 v24, v24
	s_nop 0
	v_add_f32_e32 v24, 1.0, v24
	v_rcp_f32_e32 v24, v24
	s_nop 0
	v_pk_mul_f32 v[22:23], v[22:23], v[24:25]
	ds_write2_b32 v34, v22, v23 offset1:1
	v_pk_fma_f32 v[22:23], v[2:3], v[32:33], 0 op_sel_hi:[1,1,0]
	s_nop 0
	v_pk_fma_f32 v[22:23], v[4:5], v[20:21], v[22:23]
	v_pk_fma_f32 v[20:21], v[2:3], v[20:21], 0 op_sel_hi:[1,1,0]
	v_pk_fma_f32 v[22:23], v[6:7], v[18:19], v[22:23]
	v_pk_fma_f32 v[20:21], v[4:5], v[18:19], v[20:21]
	v_pk_fma_f32 v[22:23], v[8:9], v[10:11], v[22:23]
	v_pk_fma_f32 v[20:21], v[6:7], v[10:11], v[20:21]
	v_mul_f32_e32 v24, 0xbfb8aa3b, v23
	v_exp_f32_e32 v24, v24
	v_pk_fma_f32 v[20:21], v[8:9], v[12:13], v[20:21]
	v_pk_fma_f32 v[18:19], v[2:3], v[18:19], 0 op_sel_hi:[1,1,0]
	v_pk_fma_f32 v[2:3], v[2:3], v[10:11], 0 op_sel_hi:[1,1,0]
	v_add_f32_e32 v24, 1.0, v24
	v_rcp_f32_e32 v25, v24
	v_mul_f32_e32 v24, 0xbfb8aa3b, v22
	v_exp_f32_e32 v24, v24
	v_pk_fma_f32 v[18:19], v[4:5], v[10:11], v[18:19]
	v_pk_fma_f32 v[2:3], v[4:5], v[12:13], v[2:3]
	v_pk_fma_f32 v[18:19], v[6:7], v[12:13], v[18:19]
	v_add_f32_e32 v24, 1.0, v24
	v_rcp_f32_e32 v24, v24
	v_pk_fma_f32 v[2:3], v[6:7], v[14:15], v[2:3]
	v_pk_fma_f32 v[18:19], v[8:9], v[14:15], v[18:19]
	v_pk_fma_f32 v[2:3], v[8:9], v[16:17], v[2:3]
	v_pk_mul_f32 v[22:23], v[22:23], v[24:25]
	ds_write_b64 v30, v[22:23]
	v_mul_f32_e32 v22, 0xbfb8aa3b, v21
	v_exp_f32_e32 v22, v22
	v_add_u32_e32 v24, s9, v0
	v_mul_f32_e32 v4, 0xbfb8aa3b, v3
	v_exp_f32_e32 v4, v4
	v_add_f32_e32 v22, 1.0, v22
	v_rcp_f32_e32 v23, v22
	v_mul_f32_e32 v22, 0xbfb8aa3b, v20
	v_exp_f32_e32 v22, v22
	v_add_f32_e32 v4, 1.0, v4
	v_rcp_f32_e32 v5, v4
	v_mul_f32_e32 v4, 0xbfb8aa3b, v2
	v_add_f32_e32 v22, 1.0, v22
	v_rcp_f32_e32 v22, v22
	v_exp_f32_e32 v4, v4
	v_pk_mul_f32 v[20:21], v[20:21], v[22:23]
	ds_write2_b32 v24, v20, v21 offset1:1
	v_mul_f32_e32 v20, 0xbfb8aa3b, v19
	v_exp_f32_e32 v20, v20
	v_add_f32_e32 v4, 1.0, v4
	v_rcp_f32_e32 v4, v4
	v_add_u32_e32 v22, s11, v0
	v_add_f32_e32 v20, 1.0, v20
	v_rcp_f32_e32 v21, v20
	v_mul_f32_e32 v20, 0xbfb8aa3b, v18
	v_exp_f32_e32 v20, v20
	v_add_u32_e32 v0, s14, v0
	s_and_b64 s[14:15], s[6:7], exec
	v_pk_mul_f32 v[2:3], v[2:3], v[4:5]
	v_add_f32_e32 v20, 1.0, v20
	v_rcp_f32_e32 v20, v20
	s_cselect_b32 s9, 0x4400, 0
	s_lshl_b32 s11, s43, 4
	s_add_i32 s9, s9, 0
	v_pk_mul_f32 v[18:19], v[18:19], v[20:21]
	ds_write_b64 v22, v[18:19]
	ds_write2_b32 v0, v2, v3 offset1:1
	v_or_b32_e32 v0, s11, v38
	v_mul_u32_u24_e32 v0, 0x110, v0
	v_and_b32_e32 v20, 48, v26
	v_add3_u32 v0, s9, v0, v20
	s_waitcnt lgkmcnt(0)
	s_barrier
; #define LAS __attribute__((address_space(3)))
; DI void gdn_prep_item(LAS unsigned char* lds, const Ctx& c, int l, int item) {
;     ...
;         const int mat = wave >> 2, rb = wave & 3, m16 = lane & 15, g4 = lane >> 4;
;         const LAS unsigned char* Ab = lds + (mat == 0 ? GP_KB : GP_QB) + (16 * rb + m16) * 272 + g4 * 16;
;         bf16x8 af[4];
; #pragma unroll
;         for (int ks = 0; ks < 4; ++ks) af[ks] = lds_frag16(Ab + ks * 64);
;         bf16_t* ATg = (bf16_t*)(ws + WS_AT) + cidx * 4096;
;         for (int cb = 0; cb <= rb; ++cb) {
;             f32x4 d = {0.f, 0.f, 0.f, 0.f};
;             const LAS unsigned char* Bb = lds + GP_KB + (16 * cb + m16) * 272 + g4 * 16;
; #pragma unroll
;             for (int ks = 0; ks < 4; ++ks) d = __builtin_amdgcn_mfma_f32_16x16x32_bf16(af[ks], lds_frag16(Bb + ks * 64), d, 0, 0, 0);
;             const int j = 16 * cb + m16; const float gj = gL[j];
;             f32x4 lv;
	ds_read_b128 v[2:5], v0
	ds_read_b128 v[6:9], v0 offset:64
	ds_read_b128 v[10:13], v0 offset:128
	ds_read_b128 v[14:17], v0 offset:192
	v_lshrrev_b32_e32 v0, 2, v26
	v_and_or_b32 v40, v0, 12, s11
	v_lshlrev_b32_e32 v0, 2, v40
	s_add_i32 s14, 0, 0x1cb00
	s_add_i32 s42, 0, 0x1ca00
	v_or_b32_e32 v43, 1, v40
	v_add_u32_e32 v41, s14, v0
	v_add_u32_e32 v42, s42, v0
	v_lshlrev_b32_e32 v0, 2, v43
	v_or_b32_e32 v46, 2, v40
	v_add_u32_e32 v44, s14, v0
	v_add_u32_e32 v45, s42, v0
	v_lshlrev_b32_e32 v0, 2, v46
	v_or_b32_e32 v49, 3, v40
	v_add_u32_e32 v47, s14, v0
	v_add_u32_e32 v48, s42, v0
	v_lshlrev_b32_e32 v0, 2, v49
	s_lshl_b32 s9, s43, 5
	v_add_u32_e32 v50, s14, v0
	v_add_u32_e32 v51, s42, v0
	s_add_u32 s44, s9, 32
	v_lshlrev_b32_e32 v0, 8, v38
	s_lshl_b32 s9, s43, 6
	v_or3_b32 v0, v0, s9, v20
	v_readlane_b32 s9, v254, 5
	s_or_b32 s8, s24, s8
	v_mov_b32_e32 v19, v1
	v_add_u32_e32 v52, s9, v0
	s_ashr_i32 s9, s8, 31
	s_lshl_b64 s[8:9], s[8:9], 20
	v_lshlrev_b32_e32 v0, 4, v26
	s_or_b32 s8, s8, s10
	s_lshl_b32 s10, s43, 10
	v_and_b32_e32 v39, 0x300, v0
	v_or3_b32 v0, s10, v39, v38
	v_lshlrev_b32_e32 v18, 1, v0
	s_add_u32 s10, s97, s8
	v_or_b32_e32 v0, 0x180, v18
	s_addc_u32 s11, s60, s9
	v_lshl_add_u64 v[30:31], s[10:11], 0, v[0:1]
	v_or_b32_e32 v0, 0x100, v18
	v_lshl_add_u64 v[32:33], s[10:11], 0, v[0:1]
	v_or_b32_e32 v0, 0x80, v18
	v_lshl_add_u64 v[34:35], s[10:11], 0, v[0:1]
	v_lshl_add_u64 v[36:37], s[10:11], 0, v[18:19]
	v_mul_u32_u24_e32 v18, 0x110, v38
	s_add_i32 s10, 0, 0x4400
	v_lshl_add_u32 v0, v38, 2, s14
	v_add3_u32 v53, v18, v20, s10
	s_mov_b64 s[10:11], 0
	s_branch .LBB0_280
